# weight conversion: LayerNorm gain/bias values for the next K tile prefetched with the weight tile instead of loaded and waited inside the iteration
# baseline (speedup 1.0000x reference)
; #define LAS __attribute__((address_space(3)))
; DI int lane_id_() { int l; asm volatile("v_mbcnt_lo_u32_b32 %0, -1, 0\n\tv_mbcnt_hi_u32_b32 %0, -1, %0" : "=v"(l)); return l; }
;   if (kend < 0) kend = K;
;   LAS bf16_t* tile = (LAS bf16_t*)lds;
;   LAS float* red = (LAS float*)(lds + 64 * 72 * 2);
;   int tid_ = wv * 64 + lane_id_(); asm volatile("" : "+v"(tid_)); const int tid = tid_, kr = tid >> 4, nc = (tid & 15) * 4;
;   const bool colok = (n0 + nc) < nvalid;
;   float s1[4] = {0.f, 0.f, 0.f, 0.f}, s2[4] = {0.f, 0.f, 0.f, 0.f};
;   f32x4 w[2];
; #pragma unroll
;   for (int rr = 0; rr < 2; ++rr) w[rr] = colok ? *(const f32x4*)(src + (size_t)(kbeg + kr + rr * 32) * ldn + n0 + nc) : (f32x4){0.f, 0.f, 0.f, 0.f};
.LBB0_82:
	s_or_b64 exec, exec, s[0:1]
	v_ashrrev_i32_e32 v8, 3, v33
	v_lshlrev_b32_e32 v9, 2, v8
	v_lshrrev_b32_e32 v12, 1, v8
	v_mul_lo_u32 v13, v8, s90
	v_and_b32_e32 v8, 35, v8
	v_and_b32_e32 v9, 16, v9
	v_and_b32_e32 v12, 12, v12
	v_add_u32_e32 v8, s26, v8
	v_add3_u32 v8, v8, v9, v12
	v_mov_b32_e32 v9, v32
	v_lshlrev_b64 v[8:9], 11, v[8:9]
	v_and_b32_e32 v12, 7, v33
	s_mov_b32 s27, s85
	v_lshl_or_b32 v8, v12, 4, v8
	s_lshl_b64 s[0:1], s[26:27], 2
	v_lshl_add_u64 v[28:29], s[24:25], 0, v[8:9]
	v_add_u32_e32 v8, 64, v24
	v_mad_i64_i32 v[30:31], s[30:31], s77, v8, 0
	v_and_b32_e32 v8, 15, v33
	s_add_u32 s0, s49, s0
	v_lshlrev_b32_e32 v8, 4, v8
	v_mov_b32_e32 v9, v32
	s_addc_u32 s1, s43, s1
	v_lshl_add_u64 v[34:35], s[0:1], 0, v[8:9]
	v_add_u32_e32 v8, 0x60, v24
	v_mad_i64_i32 v[36:37], s[0:1], s77, v8, 0
	v_ashrrev_i32_e32 v25, 31, v24
	v_readlane_b32 s0, v255, 18
	v_lshlrev_b64 v[8:9], 2, v[24:25]
	v_readlane_b32 s1, v255, 19
	v_lshlrev_b32_e32 v14, 4, v33
	v_lshl_add_u32 v11, v24, 1, 0
	v_lshl_add_u64 v[38:39], s[0:1], 0, v[8:9]
	v_readlane_b32 s0, v255, 16
	v_readlane_b32 s1, v255, 17
	v_and_b32_e32 v14, 0x70, v14
	v_mul_u32_u24_e32 v10, 0x90, v10
	v_lshl_add_u64 v[40:41], s[0:1], 0, v[8:9]
	v_mov_b32_e32 v8, 0
	v_add3_u32 v27, 0, v13, v14
	s_mov_b32 s27, 0
	v_add_u32_e32 v25, v11, v10
	v_mov_b32_e32 v9, 0
	v_mov_b32_e32 v10, 0
	v_mov_b32_e32 v11, 0
	v_mov_b32_e32 v12, 0
	v_mov_b32_e32 v13, v8
	v_mov_b32_e32 v14, 0
	v_mov_b32_e32 v15, v8
	s_and_b64 vcc, exec, s[4:5]
	s_cbranch_vccz .Lconv83_ng0
	global_load_dword v216, v[40:41], off
	global_load_dword v218, v[40:41], off offset:128
.Lconv83_ng0:
	s_and_b64 vcc, exec, s[72:73]
	s_cbranch_vccz .Lconv83_nb0
	global_load_dword v217, v[38:39], off
	global_load_dword v219, v[38:39], off offset:128

; DI float h2f(bf16_t v) { return (float)__builtin_bit_cast(_Float16, v); }
; DI float bf2f(bf16_t v) { return __uint_as_float(((unsigned)v) << 16); }
; DI void lds_barrier() { asm volatile("s_waitcnt lgkmcnt(0)\n\ts_barrier" ::: "memory"); }
;     ...
;   for (int k0 = kbeg; k0 < kend; k0 += 64) {
;     lds_barrier();
; #pragma unroll
;     for (int rr = 0; rr < 2; ++rr) { const int k = k0 + kr + rr * 32; const float gk = g ? g[k] : 1.0f, bk = b ? b[k] : 0.0f;
; #pragma unroll
;       for (int j = 0; j < 4; ++j) { const bf16_t v = perm ? f2h(w[rr][j] * gk) : f2bf(w[rr][j] * gk); tile[(nc + j) * 72 + kr + rr * 32] = v; s1[j] += perm ? h2f(v) : bf2f(v); s2[j] += bk * w[rr][j]; } }
;     if (k0 + 64 < kend) {
; #pragma unroll
;       for (int rr = 0; rr < 2; ++rr) w[rr] = colok ? *(const f32x4*)(src + (size_t)(k0 + 64 + kr + rr * 32) * ldn + n0 + nc) : (f32x4){0.f, 0.f, 0.f, 0.f};
;     }
.LBB0_83:
	s_waitcnt lgkmcnt(0)
	s_barrier
	v_mov_b32_e32 v16, 1.0
	s_and_b64 vcc, exec, s[4:5]
	s_cbranch_vccz .LBB0_85
	v_mov_b32_e32 v16, v216
.LBB0_85:
	v_cndmask_b32_e64 v17, 0, 1, s[72:73]
	v_cmp_ne_u32_e64 s[0:1], 1, v17
	s_andn2_b64 vcc, exec, s[72:73]
	v_mov_b32_e32 v42, 0
	s_cbranch_vccnz .LBB0_87
	v_mov_b32_e32 v42, v217
.LBB0_87:
	s_waitcnt vmcnt(0)
	v_fma_mixlo_f16 v43, v0, v16, 0
	v_fma_mixlo_f16 v45, v1, v16, 0
	v_fma_mixlo_f16 v46, v2, v16, 0
	v_fma_mixlo_f16 v47, v3, v16, 0
	s_andn2_b64 vcc, exec, s[4:5]
	v_mov_b32_e32 v16, 1.0
	ds_write_b16 v25, v43
	ds_write_b16 v25, v45 offset:144
	ds_write_b16 v25, v46 offset:288
	ds_write_b16 v25, v47 offset:432
	s_cbranch_vccnz .LBB0_89
	v_mov_b32_e32 v16, v218
.LBB0_89:
	s_and_b64 vcc, exec, s[0:1]
	v_mov_b32_e32 v44, 0
	s_cbranch_vccnz .LBB0_91
	v_mov_b32_e32 v44, v219
.LBB0_91:
	s_cmpk_gt_u32 s27, 0x3bf
	s_waitcnt vmcnt(0)
	v_fma_mixlo_f16 v48, v4, v16, 0
	v_fma_mixlo_f16 v49, v5, v16, 0
	v_fma_mixlo_f16 v50, v6, v16, 0
	v_fma_mixlo_f16 v51, v7, v16, 0
	s_cselect_b64 s[0:1], -1, 0
	s_cmpk_lt_u32 s27, 0x3c0
	v_mov_b32_e32 v19, v7
	v_mov_b32_e32 v18, v6
	v_mov_b32_e32 v17, v5
	v_mov_b32_e32 v16, v4
	v_mov_b32_e32 v23, v3
	v_mov_b32_e32 v22, v2
	v_mov_b32_e32 v21, v1
	v_mov_b32_e32 v20, v0
	ds_write_b16 v25, v48 offset:64
	ds_write_b16 v25, v49 offset:208
	ds_write_b16 v25, v50 offset:352
	ds_write_b16 v25, v51 offset:496
	s_cbranch_scc0 .LBB0_97
	s_and_b64 vcc, exec, s[4:5]
	s_cbranch_vccz .Lconv83_ng
	global_load_dword v216, v[40:41], off offset:256
	global_load_dword v218, v[40:41], off offset:384
.Lconv83_ng:
	s_and_b64 vcc, exec, s[72:73]
	s_cbranch_vccz .Lconv83_nb
	global_load_dword v217, v[38:39], off offset:256
	global_load_dword v219, v[38:39], off offset:384
.Lconv83_nb:
	v_mov_b32_e32 v16, 0
	v_mov_b32_e32 v20, 0
	v_mov_b32_e32 v21, 0
	v_mov_b32_e32 v22, 0
	v_mov_b32_e32 v23, 0
	s_and_saveexec_b64 s[30:31], s[6:7]
	s_cbranch_execz .LBB0_94
	v_lshl_add_u64 v[18:19], v[34:35], 0, v[30:31]
	global_load_dwordx4 v[20:23], v[18:19], off

; DI int lane_id_() { int l; asm volatile("v_mbcnt_lo_u32_b32 %0, -1, 0\n\tv_mbcnt_hi_u32_b32 %0, -1, %0" : "=v"(l)); return l; }
;     ...
;   int tid_ = wv * 64 + lane_id_(); asm volatile("" : "+v"(tid_)); const int tid = tid_, kr = tid >> 4, nc = (tid & 15) * 4;
;   const bool colok = (n0 + nc) < nvalid;
;   float s1[4] = {0.f, 0.f, 0.f, 0.f}, s2[4] = {0.f, 0.f, 0.f, 0.f};
;   f32x4 w[2];
; #pragma unroll
;   for (int rr = 0; rr < 2; ++rr) w[rr] = colok ? *(const f32x4*)(src + (size_t)(kbeg + kr + rr * 32) * ldn + n0 + nc) : (f32x4){0.f, 0.f, 0.f, 0.f};
; DI void convert_phase(int wv, const P& p_, int L, LAS unsigned char* lds) {
;     ...
;       const int f = j / 136, jj = j % 136;
;       const float* lg = p.ln_gain + (size_t)(L * 3 + (f == 0 ? -1 : 1)) * DM; const float* lbias = p.ln_bias + (size_t)(L * 3 + (f == 0 ? -1 : 1)) * DM;
;       const bool fold = !(L == 0 && f == 0);
;       float* cbase = (float*)(ws + (f == 0 ? C_GU1 : C_GU2));
;       if (jj < 88) {
;         const int up = jj / 44, s = jj % 44, n0 = s * 64;
;         const float* src = (f == 0 ? (up ? p.f1u : p.f1g) : (up ? p.f2u : p.f2g)) + (size_t)L * DM * DFF;
;         conv_strip(wv, lds, src, DFF, DM, n0, DFF, (bf16_t*)(ws + (f == 0 ? W_GU1 : W_GU2)), (n0 >> 7) * 256 + (n0 & 127) + up * 128, fold ? lg : nullptr, fold ? lbias : nullptr, cbase, cbase + 5632);
.LBB0_111:
	s_and_b64 vcc, exec, s[0:1]
	s_cbranch_vccz .LBB0_38
	s_sext_i32_i16 s29, s27
	s_and_b64 s[0:1], s[78:79], exec
	s_mulk_i32 s29, 0xba3
	s_cselect_b32 s90, -1, 1
	s_lshr_b32 s30, s29, 31
	s_ashr_i32 s29, s29, 17
	s_add_i32 s29, s29, s30
	s_sext_i32_i16 s35, s29
	s_mul_i32 s29, s29, 44
	s_sub_i32 s29, s27, s29
	s_sext_i32_i16 s29, s29
	s_and_b64 s[0:1], s[46:47], s[78:79]
	s_lshl_b32 s34, s29, 6
	s_add_i32 s27, s27, 43
	v_readlane_b32 s60, v252, 16
	v_readlane_b32 s4, v252, 32
	s_cmpk_lt_u32 s27, 0x57
	v_readlane_b32 s68, v252, 24
	v_readlane_b32 s69, v252, 25
	v_readlane_b32 s70, v252, 26
	v_readlane_b32 s71, v252, 27
	v_readlane_b32 s74, v252, 30
	v_readlane_b32 s75, v252, 31
	v_readlane_b32 s5, v252, 33
	s_cselect_b32 s27, s68, s70
	s_cselect_b32 s36, s69, s71
	s_cselect_b32 s37, s74, s4
	s_cselect_b32 s38, s75, s5
	s_and_b64 s[30:31], s[78:79], exec
	s_cselect_b32 s92, s27, s37
	s_mov_b32 s69, s48
	s_cselect_b32 s30, 0, 0x1080000
	s_cselect_b32 s91, s36, s38
	s_add_u32 s31, s92, s93
	s_addc_u32 s37, s91, 0
	s_lshl_b32 s27, s29, 7
	s_lshl_b32 s84, s35, 7
	s_waitcnt vmcnt(1)
	v_mbcnt_lo_u32_b32 v0, -1, 0
	v_mbcnt_hi_u32_b32 v0, -1, v0
	s_ashr_i32 s35, s34, 31
	v_add_u32_e32 v33, s69, v0
	s_and_b32 s27, s27, 0xffffff00
	s_and_b32 s29, s34, 64
	s_lshl_b64 s[34:35], s[34:35], 2
	v_lshlrev_b32_e32 v0, 2, v33
	v_and_b32_e32 v10, 60, v0
	s_add_u32 s36, s31, s34
	v_ashrrev_i32_e32 v24, 4, v33
	s_addc_u32 s37, s37, s35
	v_lshlrev_b32_e32 v26, 2, v10
	v_mov_b32_e32 v27, v32
	v_lshl_add_u64 v[0:1], s[36:37], 0, v[26:27]
	s_movk_i32 s4, 0x2c00
	v_add_u32_e32 v4, 32, v24
	v_mad_i64_i32 v[2:3], s[36:37], v24, s4, v[0:1]
	v_mad_i64_i32 v[4:5], s[36:37], v4, s4, v[0:1]
	global_load_dwordx4 v[0:3], v[2:3], off
	s_nop 0
	global_load_dwordx4 v[4:7], v[4:5], off
	v_readlane_b32 s6, v252, 34
	v_readlane_b32 s7, v252, 35
	v_mad_i64_i32 v[8:9], s[36:37], v24, s4, 0
	v_readlane_b32 s4, v252, 54
	v_readlane_b32 s6, v252, 58
	s_movk_i32 vcc_lo, 0x90
	v_readlane_b32 s5, v252, 55
	v_readlane_b32 s7, v252, 59
	v_ashrrev_i32_e32 v11, 3, v33
	v_lshlrev_b32_e32 v16, 4, v33
	s_nor_b64 s[36:37], s[0:1], s[4:5]
	s_nor_b64 s[38:39], s[0:1], s[6:7]
	v_mul_lo_u32 v15, v11, vcc_lo
	v_and_b32_e32 v16, 0x70, v16
	s_add_i32 s0, s84, s27
	v_lshlrev_b32_e32 v13, 2, v11
	v_lshrrev_b32_e32 v14, 1, v11
	v_add3_u32 v27, 0, v15, v16
	v_mul_u32_u24_e32 v15, 0x90, v10
	v_and_or_b32 v10, v11, 35, s0
	v_and_b32_e32 v13, 16, v13
	v_and_b32_e32 v14, 12, v14
	v_or_b32_e32 v10, s29, v10
	v_or3_b32 v10, v10, v13, v14
	v_ashrrev_i32_e32 v11, 31, v10
	s_mov_b32 s31, 0
	v_lshlrev_b64 v[10:11], 11, v[10:11]
	v_lshl_add_u64 v[10:11], s[30:31], 0, v[10:11]
	v_and_b32_e32 v13, 7, v33
	v_lshl_or_b32 v10, v13, 4, v10
	v_readlane_b32 s0, v255, 10
	v_lshl_add_u64 v[28:29], s[94:95], 0, v[10:11]
	v_readlane_b32 s1, v255, 11
	s_add_u32 s0, s92, s0
	v_and_b32_e32 v10, 15, v33
	s_addc_u32 s1, s91, s1
	v_lshl_or_b32 v8, v10, 4, v8
	v_lshl_add_u64 v[30:31], s[0:1], 0, v[8:9]
	v_readlane_b32 s0, v255, 12
	v_readlane_b32 s1, v255, 13
	s_add_u32 s0, s92, s0
	s_addc_u32 s1, s91, s1
	v_lshl_add_u64 v[34:35], s[0:1], 0, v[8:9]
	v_readlane_b32 s0, v255, 5
	s_add_i32 s0, s0, s90
	s_ashr_i32 s1, s0, 31
	v_ashrrev_i32_e32 v25, 31, v24
	s_lshl_b64 s[0:1], s[0:1], 12
	v_lshl_add_u64 v[8:9], v[24:25], 2, s[0:1]
	v_readlane_b32 s0, v254, 2
	v_readlane_b32 s1, v254, 3
	v_readlane_b32 s72, v252, 28
	v_readlane_b32 s73, v252, 29
	v_lshl_add_u64 v[36:37], s[0:1], 0, v[8:9]
	v_readlane_b32 s0, v254, 4
	v_readlane_b32 s1, v254, 5
	v_readlane_b32 s64, v252, 20
	v_readlane_b32 s65, v252, 21
	v_readlane_b32 s66, v252, 22
	v_readlane_b32 s67, v252, 23
	v_readlane_b32 s72, v255, 24
	v_readlane_b32 s4, v252, 56
	v_lshl_add_u32 v12, v24, 1, 0
	v_lshl_add_u64 v[38:39], s[0:1], 0, v[8:9]
	v_mov_b32_e32 v8, 0
	s_mov_b32 s60, 0xf149f2ca
	s_movk_i32 s65, 0xa00
	v_readlane_b32 s64, v255, 30
	v_readlane_b32 s67, v255, 26
	v_readlane_b32 s73, v255, 25
	v_readlane_b32 s66, v255, 23
	s_mov_b32 s68, s44
	v_readlane_b32 s74, v255, 27
	v_readlane_b32 s75, v255, 28
	v_readlane_b32 s5, v252, 57
	s_movk_i32 s91, 0x1600
	s_movk_i32 s90, 0x90
	v_add_u32_e32 v25, v12, v15
	v_mov_b32_e32 v9, v8
	v_mov_b32_e32 v10, v8
	v_mov_b32_e32 v11, v8
	v_mov_b32_e32 v12, v8
	v_mov_b32_e32 v13, v8
	v_mov_b32_e32 v14, v8
	v_mov_b32_e32 v15, v8
	s_mov_b64 s[6:7], 0xb0000
	v_readlane_b32 s61, v252, 17
	v_readlane_b32 s62, v252, 18
	v_readlane_b32 s63, v252, 19
	v_readlane_b32 s8, v252, 36
	v_readlane_b32 s9, v252, 37
	v_readlane_b32 s10, v252, 38
	v_readlane_b32 s11, v252, 39
	v_readlane_b32 s12, v252, 40
	v_readlane_b32 s13, v252, 41
	v_readlane_b32 s14, v252, 42
	v_readlane_b32 s15, v252, 43
	v_readlane_b32 s16, v252, 44
	v_readlane_b32 s17, v252, 45
	v_readlane_b32 s18, v252, 46
	v_readlane_b32 s19, v252, 47
	s_and_b64 vcc, exec, s[36:37]
	s_cbranch_vccz .Lconv113_ng0
	global_load_dword v216, v[38:39], off offset:-128
	global_load_dword v218, v[38:39], off
.Lconv113_ng0:
	s_and_b64 vcc, exec, s[38:39]
	s_cbranch_vccz .Lconv113_nb0
	global_load_dword v217, v[36:37], off offset:-128
	global_load_dword v219, v[36:37], off

; DI float h2f(bf16_t v) { return (float)__builtin_bit_cast(_Float16, v); }
; DI float bf2f(bf16_t v) { return __uint_as_float(((unsigned)v) << 16); }
; DI void lds_barrier() { asm volatile("s_waitcnt lgkmcnt(0)\n\ts_barrier" ::: "memory"); }
;     ...
;   for (int k0 = kbeg; k0 < kend; k0 += 64) {
;     lds_barrier();
; #pragma unroll
;     for (int rr = 0; rr < 2; ++rr) { const int k = k0 + kr + rr * 32; const float gk = g ? g[k] : 1.0f, bk = b ? b[k] : 0.0f;
; #pragma unroll
;       for (int j = 0; j < 4; ++j) { const bf16_t v = perm ? f2h(w[rr][j] * gk) : f2bf(w[rr][j] * gk); tile[(nc + j) * 72 + kr + rr * 32] = v; s1[j] += perm ? h2f(v) : bf2f(v); s2[j] += bk * w[rr][j]; } }
;     if (k0 + 64 < kend) {
; #pragma unroll
;       for (int rr = 0; rr < 2; ++rr) w[rr] = colok ? *(const f32x4*)(src + (size_t)(k0 + 64 + kr + rr * 32) * ldn + n0 + nc) : (f32x4){0.f, 0.f, 0.f, 0.f};
;     }
.LBB0_113:
	s_waitcnt lgkmcnt(0)
	s_barrier
	v_mov_b32_e32 v16, 1.0
	s_and_b64 vcc, exec, s[36:37]
	s_cbranch_vccz .LBB0_115
	v_mov_b32_e32 v16, v216
.LBB0_115:
	v_cndmask_b32_e64 v17, 0, 1, s[38:39]
	v_cmp_ne_u32_e64 s[0:1], 1, v17
	s_andn2_b64 vcc, exec, s[38:39]
	v_mov_b32_e32 v40, 0
	s_cbranch_vccnz .LBB0_117
	v_mov_b32_e32 v40, v217
.LBB0_117:
	s_waitcnt vmcnt(0)
	v_fma_mixlo_f16 v41, v0, v16, 0
	v_fma_mixlo_f16 v43, v1, v16, 0
	v_fma_mixlo_f16 v44, v2, v16, 0
	v_fma_mixlo_f16 v45, v3, v16, 0
	s_andn2_b64 vcc, exec, s[36:37]
	v_mov_b32_e32 v16, 1.0
	ds_write_b16 v25, v41
	ds_write_b16 v25, v43 offset:144
	ds_write_b16 v25, v44 offset:288
	ds_write_b16 v25, v45 offset:432
	s_cbranch_vccnz .LBB0_119
	v_mov_b32_e32 v16, v218
.LBB0_119:
	s_and_b64 vcc, exec, s[0:1]
	v_mov_b32_e32 v42, 0
	s_cbranch_vccnz .LBB0_121
	v_mov_b32_e32 v42, v219
.LBB0_121:
	s_cmpk_gt_u32 s31, 0x3bf
	s_waitcnt vmcnt(0)
	v_fma_mixlo_f16 v46, v4, v16, 0
	v_fma_mixlo_f16 v47, v5, v16, 0
	v_fma_mixlo_f16 v48, v6, v16, 0
	v_fma_mixlo_f16 v49, v7, v16, 0
	s_cselect_b64 s[0:1], -1, 0
	s_cmpk_lt_u32 s31, 0x3c0
	v_mov_b32_e32 v16, v0
	v_mov_b32_e32 v17, v1
	v_mov_b32_e32 v18, v2
	v_mov_b32_e32 v19, v3
	v_mov_b32_e32 v20, v4
	v_mov_b32_e32 v21, v5
	v_mov_b32_e32 v22, v6
	v_mov_b32_e32 v23, v7
	ds_write_b16 v25, v46 offset:64
	ds_write_b16 v25, v47 offset:208
	ds_write_b16 v25, v48 offset:352
	ds_write_b16 v25, v49 offset:496
	s_cbranch_scc0 .LBB0_123
	s_and_b64 vcc, exec, s[36:37]
	s_cbranch_vccz .Lconv113_ng
	global_load_dword v216, v[38:39], off offset:128
	global_load_dword v218, v[38:39], off offset:256
.Lconv113_ng:
	s_and_b64 vcc, exec, s[38:39]
	s_cbranch_vccz .Lconv113_nb
	global_load_dword v217, v[36:37], off offset:128
	global_load_dword v219, v[36:37], off offset:256
.Lconv113_nb:
	v_lshl_add_u64 v[16:17], v[34:35], 0, s[34:35]
	v_lshl_add_u64 v[20:21], v[30:31], 0, s[34:35]
	global_load_dwordx4 v[16:19], v[16:17], off
	s_nop 0
	global_load_dwordx4 v[20:23], v[20:21], off
